# attention loop back-edge rotation: next-tile scalar setup and LDS address computed before the tile barrier, LDS reads first after release, K/V global fetch issued after them
# baseline (speedup 1.0000x reference)
; #define LAS __attribute__((address_space(3)))
; template <bool NA> ...
;     ...
;     for (int j = 0; j < ntiles; ++j) {
;         const int cur = j & 1;
;         if (j + 1 < ntiles) { const int t0 = (j + 1) < 4 ? SEQ + 64 * (j + 1) : loc_base + 64 * (j + 1 - 4);
;             kreg = *(const u32x4*)(PB + (size_t)(t0 + srow) * INW + kcol + 8 * sch); vreg = *(const u32x4*)(VT + (size_t)srow * NTOK + t0 + 8 * sch); }
;         bool active = true; int kr = 0;
;         if (NA && j >= 4) { kr = na_rs_base + (j - 4); active = (kr >= na_rs) && (kr < na_rs + 8); }
;         if (active) {
;     ...
;                 for (int r = 0; r < 16; ++r) { o0[r] *= alpha; o1[r] *= alpha; p0[r] -= delta; p1[r] -= delta; negm[r] = -m; }
;             }
;             float ls = 0.f;
; #pragma unroll
;             for (int r = 0; r < 16; ++r) { p0[r] = __builtin_amdgcn_exp2f(p0[r]); p1[r] = __builtin_amdgcn_exp2f(p1[r]); ls += p0[r] + p1[r]; }
;             l += ls;
;             bf16x8 pb[4];
;             { u32x4 w;
;               w.x = pk2(p0[0], p0[1]); w.y = pk2(p0[2], p0[3]); w.z = pk2(p0[4], p0[5]); w.w = pk2(p0[6], p0[7]); pb[0] = __builtin_bit_cast(bf16x8, w);
;               w.x = pk2(p0[8], p0[9]); w.y = pk2(p0[10], p0[11]); w.z = pk2(p0[12], p0[13]); w.w = pk2(p0[14], p0[15]); pb[1] = __builtin_bit_cast(bf16x8, w);
;               w.x = pk2(p1[0], p1[1]); w.y = pk2(p1[2], p1[3]); w.z = pk2(p1[4], p1[5]); w.w = pk2(p1[6], p1[7]); pb[2] = __builtin_bit_cast(bf16x8, w);
;               w.x = pk2(p1[8], p1[9]); w.y = pk2(p1[10], p1[11]); w.z = pk2(p1[12], p1[13]); w.w = pk2(p1[14], p1[15]); pb[3] = __builtin_bit_cast(bf16x8, w); }
; #pragma unroll
;             for (int s = 0; s < 4; ++s) {
;                 const bf16x8 vf0 = vfr[2 * s], vf1 = vfr[2 * s + 1];
;                 o0 = __builtin_amdgcn_mfma_f32_32x32x16_bf16(vf0, pb[s], o0, 0, 0, 0);
;                 o1 = __builtin_amdgcn_mfma_f32_32x32x16_bf16(vf1, pb[s], o1, 0, 0, 0);
;             }
;         }
;         if (j + 1 < ntiles) {
;             *(LAS u32x4*)(lds + (cur ^ 1) * KB + srow * 144 + sch * 16) = kreg;
;             LAS unsigned char* vp = lds + VOFF + (cur ^ 1) * VB + srow * 144 + (sch >> 1) * 32 + (sch & 1) * 8;
;             *(LAS u32x2*)vp = (u32x2){vreg.x, vreg.y}; *(LAS u32x2*)(vp + 16) = (u32x2){vreg.z, vreg.w};
;         }
;         __syncthreads();
.LBB0_303:
	v_exp_f32_e32 v124, v66
	v_exp_f32_e32 v125, v50
	v_exp_f32_e32 v16, v67
	v_exp_f32_e32 v66, v51
	v_mov_b32_e32 v17, v1
	v_add_f32_e32 v67, v125, v124
	s_mov_b32 s2, 0x208000
	v_pk_add_f32 v[50:51], v[66:67], v[16:17]
	v_exp_f32_e32 v17, v68
	v_pk_add_f32 v[122:123], v[50:51], v[50:51] op_sel_hi:[0,1]
	v_exp_f32_e32 v67, v52
	v_exp_f32_e32 v122, v69
	v_exp_f32_e32 v68, v53
	v_ashrrev_i32_e32 v187, 31, v186
	v_add_f32_e32 v69, v67, v17
	s_waitcnt vmcnt(1)
	ds_write_b128 v167, v[82:85] offset:9216
	s_waitcnt vmcnt(0)
	ds_write2_b64 v196, v[86:87], v[88:89] offset0:128 offset1:130
	v_pk_add_f32 v[50:51], v[68:69], v[122:123]
	v_exp_f32_e32 v69, v70
	v_pk_add_f32 v[52:53], v[50:51], v[50:51] op_sel_hi:[0,1]
	v_exp_f32_e32 v123, v54
	v_exp_f32_e32 v52, v71
	v_exp_f32_e32 v54, v55
	s_waitcnt lgkmcnt(0)
	v_add_f32_e32 v55, v123, v69
	s_barrier
	v_pk_add_f32 v[50:51], v[54:55], v[52:53]
	v_exp_f32_e32 v53, v72
	v_pk_add_f32 v[70:71], v[50:51], v[50:51] op_sel_hi:[0,1]
	v_exp_f32_e32 v55, v56
	v_exp_f32_e32 v70, v73
	v_exp_f32_e32 v56, v57
	v_cvt_pk_bf16_f32 v52, v69, v52
	v_add_f32_e32 v57, v55, v53
	v_exp_f32_e32 v69, v62
	v_pk_add_f32 v[50:51], v[56:57], v[70:71]
	v_exp_f32_e32 v57, v74
	v_pk_add_f32 v[72:73], v[50:51], v[50:51] op_sel_hi:[0,1]
	v_exp_f32_e32 v71, v58
	v_exp_f32_e32 v72, v75
	v_exp_f32_e32 v58, v59
	v_cvt_pk_bf16_f32 v53, v53, v70
	v_add_f32_e32 v59, v71, v57
	v_pk_add_f32 v[50:51], v[58:59], v[72:73]
	v_exp_f32_e32 v59, v76
	v_pk_add_f32 v[74:75], v[50:51], v[50:51] op_sel_hi:[0,1]
	v_exp_f32_e32 v73, v60
	v_exp_f32_e32 v74, v77
	v_exp_f32_e32 v60, v61
	v_add_f32_e32 v61, v73, v59
	v_pk_add_f32 v[50:51], v[60:61], v[74:75]
	s_nop 0
	v_pk_add_f32 v[76:77], v[50:51], v[50:51] op_sel_hi:[0,1]
	v_exp_f32_e32 v61, v78
	v_cvt_pk_bf16_f32 v50, v124, v16
	v_exp_f32_e32 v76, v79
	v_exp_f32_e32 v16, v63
	v_cvt_pk_bf16_f32 v51, v17, v122
	v_add_f32_e32 v17, v69, v61
	v_pk_add_f32 v[62:63], v[16:17], v[76:77]
	v_mfma_f32_32x32x16_bf16 v[34:49], v[126:129], v[50:53], v[34:49]
	v_pk_add_f32 v[62:63], v[62:63], v[62:63] op_sel_hi:[0,1]
	v_exp_f32_e32 v17, v80
	v_exp_f32_e32 v62, v81
	v_mfma_f32_32x32x16_bf16 v[18:33], v[118:121], v[50:53], v[18:33]
	v_cvt_pk_bf16_f32 v50, v57, v72
	v_cvt_pk_bf16_f32 v51, v59, v74
	v_cvt_pk_bf16_f32 v52, v61, v76
	v_cvt_pk_bf16_f32 v53, v17, v62
	s_nop 1
	v_mfma_f32_32x32x16_bf16 v[34:49], v[94:97], v[50:53], v[34:49]
	v_mfma_f32_32x32x16_bf16 v[18:33], v[114:117], v[50:53], v[18:33]
	v_cvt_pk_bf16_f32 v50, v125, v66
	v_cvt_pk_bf16_f32 v51, v67, v68
	v_cvt_pk_bf16_f32 v52, v123, v54
	v_cvt_pk_bf16_f32 v53, v55, v56
	v_cndmask_b32_e64 v54, 0, 1, s[4:5]
	v_mad_u64_u32 v[140:141], s[22:23], v54, s2, v[180:181]
	v_mfma_f32_32x32x16_bf16 v[34:49], v[90:93], v[50:53], v[34:49]
	s_mov_b32 s2, 3
	v_mfma_f32_32x32x16_bf16 v[18:33], v[12:15], v[50:53], v[18:33]
	v_exp_f32_e32 v53, v64
	v_exp_f32_e32 v52, v65
	v_cvt_pk_bf16_f32 v12, v71, v58
	v_cvt_pk_bf16_f32 v13, v73, v60
	v_cvt_pk_bf16_f32 v14, v69, v16
	v_cvt_pk_bf16_f32 v15, v53, v52
	v_add_f32_e32 v53, v53, v17
	v_lshlrev_b32_e32 v50, 7, v54
	v_mfma_f32_32x32x16_bf16 v[34:49], v[8:11], v[12:15], v[34:49]
	v_add_f32_e64 v8, v52, v62
	v_add_f32_e64 v9, v53, v63
	v_mov_b32_e32 v51, v1
	v_add_f32_e32 v8, v8, v9
	v_lshl_add_u64 v[138:139], v[178:179], 0, v[50:51]
	v_add_f32_e32 v142, v3, v8
	v_mov_b32_e32 v3, v2
	v_mov_b32_e32 v8, v2
	v_mfma_f32_32x32x16_bf16 v[18:33], v[4:7], v[12:15], v[18:33]
	v_mov_b32_e32 v4, v2
	v_mov_b32_e32 v5, v2
	v_mov_b32_e32 v6, v2
	v_mov_b32_e32 v7, v2
	v_mov_b32_e32 v9, v2
	v_mov_b32_e32 v10, v2
	v_mov_b32_e32 v11, v2
	v_mov_b32_e32 v12, v2
	v_mov_b32_e32 v13, v2
	v_mov_b32_e32 v14, v2
	v_mov_b32_e32 v15, v2
	v_mov_b32_e32 v16, v2
	v_mov_b32_e32 v17, v2
	s_cmpk_lt_u32 s2, 0x103
	s_cselect_b64 s[42:43], -1, 0
	s_and_b32 s20, s2, 1
	s_mul_i32 s22, s20, 0x2400
	v_add_u32_e32 v50, s22, v194
	s_branch .LBB0_305
.LBB0_304:
	s_add_i32 s2, s2, 1
	v_add_f32_e32 v142, v142, v50
	s_cmpk_lt_u32 s2, 0x103
	s_cselect_b64 s[42:43], -1, 0
	s_and_b32 s20, s2, 1
	s_mul_i32 s22, s20, 0x2400
	v_add_u32_e32 v50, s22, v194
	s_cmpk_lg_i32 s2, 0x104
	s_waitcnt lgkmcnt(0)
	s_barrier
	s_cbranch_scc0 .LBB0_294
.LBB0_305:
	ds_read_b128 v[66:69], v50
	ds_read_b128 v[144:147], v50 offset:32
	ds_read_b128 v[148:151], v50 offset:4608
	ds_read_b128 v[188:191], v50 offset:4640
	ds_read_b128 v[196:199], v50 offset:64
	ds_read_b128 v[218:221], v50 offset:96
	ds_read_b128 v[222:225], v50 offset:4672
	ds_read_b128 v[226:229], v50 offset:4704
	ds_read_b128 v[134:137], v50 offset:18432
	ds_read_b128 v[126:129], v50 offset:18464
	ds_read_b128 v[130:133], v50 offset:23040
	ds_read_b128 v[122:125], v50 offset:23072
	ds_read_b128 v[118:121], v50 offset:18496
	ds_read_b128 v[90:93], v50 offset:18528
	ds_read_b128 v[114:117], v50 offset:23104
	ds_read_b128 v[94:97], v50 offset:23136
	s_cmpk_gt_u32 s2, 0x102
	s_cbranch_scc1 .LBB0_307
	global_load_dwordx4 v[82:85], v[138:139], off
	global_load_dwordx4 v[86:89], v[140:141], off
; __device__ __forceinline__ float xor32_max(float v) { const auto rr = __builtin_amdgcn_permlane32_swap(__float_as_uint(v), __float_as_uint(v), false, false); return fmaxf(__uint_as_float(rr[0]), __uint_as_float(rr[1])); }
; template <bool NA> ...
;     ...
;             __builtin_amdgcn_sched_barrier(0);
;             __builtin_amdgcn_s_setprio(1);
; #pragma unroll
;             for (int s = 0; s < 4; ++s) {
;                 p0 = __builtin_amdgcn_mfma_f32_32x32x16_bf16(kf[2 * s], qb[s], p0, 0, 0, 0);
;                 p1 = __builtin_amdgcn_mfma_f32_32x32x16_bf16(kf[2 * s + 1], qb[s], p1, 0, 0, 0);
;             }
;             __builtin_amdgcn_s_setprio(0);
;             if (NA) {
;                 if (j >= 4) {
;                     const int dr = kr - na_r + 7, qc = na_qc0 + q;
; #pragma unroll
;                     for (int r = 0; r < 16; ++r) {
;                         const int kc = 8 * (r >> 2) + 4 * h + (r & 3);
;                         const bool v0 = (kc >= na_cs) && (kc < na_cs + 16), v1 = (kc + 32 >= na_cs) && (kc + 32 < na_cs + 16);
;                         const int i0 = v0 ? dr * 31 + (kc - qc + 15) : 0, i1 = v1 ? dr * 31 + (kc + 32 - qc + 15) : 0;
;                         const float b0 = biasL[i0], b1 = biasL[i1];
;                         p0[r] = v0 ? p0[r] * qs + b0 - m : -INFINITY; p1[r] = v1 ? p1[r] * qs + b1 - m : -INFINITY;
;                     }
;                 } else {
; #pragma unroll
;                     for (int r = 0; r < 16; ++r) { p0[r] = p0[r] * qs - m; p1[r] = p1[r] * qs - m; }
;                 }
;             }
;             float mx = fmaxf(fmaxf(p0[0], p1[0]), p0[1]), mx2 = fmaxf(fmaxf(p1[1], p0[2]), p1[2]);
; #pragma unroll
;             for (int r = 3; r < 15; r += 3) { mx = fmaxf(fmaxf(mx, p0[r]), p1[r]); mx2 = fmaxf(fmaxf(mx2, p0[r + 1]), p1[r + 1]); mx = fmaxf(fmaxf(mx, p0[r + 2]), p1[r + 2]); }
;             mx = fmaxf(fmaxf(mx, mx2), fmaxf(p0[15], p1[15]));
;             mx = xor32_max(mx);
;             const bool need = (mx > 0.f) || (j == 0);
;             if (__builtin_amdgcn_ballot_w64(need) != 0ull) {
;                 const float delta = need ? mx : 0.f;
;                 const float alpha = __builtin_amdgcn_exp2f(-delta);
;                 m += delta; l *= alpha;
; #pragma unroll
;                 for (int r = 0; r < 16; ++r) { o0[r] *= alpha; o1[r] *= alpha; p0[r] -= delta; p1[r] -= delta; negm[r] = -m; }
.LBB0_307:
	s_setprio 1
	s_waitcnt lgkmcnt(14)
	v_mfma_f32_32x32x16_bf16 v[50:65], v[66:69], v[98:101], v[2:17]
	v_mfma_f32_32x32x16_bf16 v[50:65], v[144:147], v[102:105], v[50:65]
	s_waitcnt lgkmcnt(13)
	v_mfma_f32_32x32x16_bf16 v[66:81], v[148:151], v[98:101], v[2:17]
	s_waitcnt lgkmcnt(12)
	v_mfma_f32_32x32x16_bf16 v[66:81], v[188:191], v[102:105], v[66:81]
	s_waitcnt lgkmcnt(11)
	v_mfma_f32_32x32x16_bf16 v[50:65], v[196:199], v[106:109], v[50:65]
	s_waitcnt lgkmcnt(9)
	v_mfma_f32_32x32x16_bf16 v[66:81], v[222:225], v[106:109], v[66:81]
	v_mfma_f32_32x32x16_bf16 v[50:65], v[218:221], v[110:113], v[50:65]
	s_waitcnt lgkmcnt(8)
	v_mfma_f32_32x32x16_bf16 v[66:81], v[226:229], v[110:113], v[66:81]
	s_setprio 0
	s_mov_b64 s[22:23], 0xd8000
	v_lshl_add_u64 v[138:139], v[138:139], 0, s[22:23]
	v_lshl_add_u64 v[140:141], v[140:141], 0, s[10:11]
	s_nop 7
	v_max3_f32 v143, v50, v66, v51
	v_max3_f32 v143, v143, v53, v69
	v_max3_f32 v143, v143, v55, v71
	v_max3_f32 v143, v143, v56, v72
	v_max3_f32 v144, v67, v52, v68
	v_max3_f32 v143, v143, v58, v74
	v_max3_f32 v144, v144, v54, v70
	v_max3_f32 v143, v143, v59, v75
	v_max3_f32 v144, v144, v57, v73
	v_max3_f32 v143, v143, v61, v77
	v_max3_f32 v144, v144, v60, v76
	v_max3_f32 v143, v143, v62, v78
	v_max3_f32 v144, v144, v63, v79
	v_max3_f32 v143, v143, v64, v80
	v_max_f32_e32 v145, v65, v81
	v_max3_f32 v143, v143, v144, v145
	v_mov_b32_e32 v144, v143
	s_nop 1
	v_permlane32_swap_b32_e32 v143, v144
	v_max_f32_e32 v143, v143, v144
	v_cmp_lt_f32_e32 vcc, 0, v143
	s_cbranch_vccz .LBB0_309
	s_nop 0
	v_cndmask_b32_e32 v4, 0, v143, vcc
	v_exp_f32_e64 v6, -v4
	v_add_f32_e32 v183, v183, v4
	v_xor_b32_e32 v2, 0x80000000, v183
	v_pk_add_f32 v[50:51], v[50:51], v[4:5] op_sel_hi:[1,0] neg_lo:[0,1] neg_hi:[0,1]
	v_pk_add_f32 v[66:67], v[66:67], v[4:5] op_sel_hi:[1,0] neg_lo:[0,1] neg_hi:[0,1]
	v_pk_add_f32 v[52:53], v[52:53], v[4:5] op_sel_hi:[1,0] neg_lo:[0,1] neg_hi:[0,1]
	v_pk_add_f32 v[68:69], v[68:69], v[4:5] op_sel_hi:[1,0] neg_lo:[0,1] neg_hi:[0,1]
	v_pk_add_f32 v[54:55], v[54:55], v[4:5] op_sel_hi:[1,0] neg_lo:[0,1] neg_hi:[0,1]
	v_pk_add_f32 v[70:71], v[70:71], v[4:5] op_sel_hi:[1,0] neg_lo:[0,1] neg_hi:[0,1]
	v_pk_add_f32 v[56:57], v[56:57], v[4:5] op_sel_hi:[1,0] neg_lo:[0,1] neg_hi:[0,1]
	v_pk_add_f32 v[72:73], v[72:73], v[4:5] op_sel_hi:[1,0] neg_lo:[0,1] neg_hi:[0,1]
	v_pk_add_f32 v[58:59], v[58:59], v[4:5] op_sel_hi:[1,0] neg_lo:[0,1] neg_hi:[0,1]
	v_pk_add_f32 v[74:75], v[74:75], v[4:5] op_sel_hi:[1,0] neg_lo:[0,1] neg_hi:[0,1]
	v_pk_add_f32 v[60:61], v[60:61], v[4:5] op_sel_hi:[1,0] neg_lo:[0,1] neg_hi:[0,1]
	v_pk_add_f32 v[76:77], v[76:77], v[4:5] op_sel_hi:[1,0] neg_lo:[0,1] neg_hi:[0,1]
	v_pk_add_f32 v[62:63], v[62:63], v[4:5] op_sel_hi:[1,0] neg_lo:[0,1] neg_hi:[0,1]
	v_pk_add_f32 v[78:79], v[78:79], v[4:5] op_sel_hi:[1,0] neg_lo:[0,1] neg_hi:[0,1]
	v_pk_mul_f32 v[48:49], v[48:49], v[6:7] op_sel_hi:[1,0]
	v_pk_mul_f32 v[46:47], v[46:47], v[6:7] op_sel_hi:[1,0]
	v_pk_mul_f32 v[44:45], v[44:45], v[6:7] op_sel_hi:[1,0]
	v_pk_mul_f32 v[42:43], v[42:43], v[6:7] op_sel_hi:[1,0]
	v_pk_mul_f32 v[40:41], v[40:41], v[6:7] op_sel_hi:[1,0]
	v_pk_mul_f32 v[38:39], v[38:39], v[6:7] op_sel_hi:[1,0]
	v_pk_mul_f32 v[36:37], v[36:37], v[6:7] op_sel_hi:[1,0]
	v_pk_mul_f32 v[34:35], v[34:35], v[6:7] op_sel_hi:[1,0]
	v_pk_mul_f32 v[32:33], v[32:33], v[6:7] op_sel_hi:[1,0]
	v_pk_mul_f32 v[30:31], v[30:31], v[6:7] op_sel_hi:[1,0]
	v_pk_mul_f32 v[28:29], v[28:29], v[6:7] op_sel_hi:[1,0]
	v_pk_mul_f32 v[26:27], v[26:27], v[6:7] op_sel_hi:[1,0]
	v_pk_mul_f32 v[24:25], v[24:25], v[6:7] op_sel_hi:[1,0]
	v_pk_mul_f32 v[22:23], v[22:23], v[6:7] op_sel_hi:[1,0]
	v_pk_mul_f32 v[20:21], v[20:21], v[6:7] op_sel_hi:[1,0]
	v_pk_mul_f32 v[18:19], v[18:19], v[6:7] op_sel_hi:[1,0]
	v_pk_add_f32 v[64:65], v[64:65], v[4:5] op_sel_hi:[1,0] neg_lo:[0,1] neg_hi:[0,1]
	v_pk_add_f32 v[80:81], v[80:81], v[4:5] op_sel_hi:[1,0] neg_lo:[0,1] neg_hi:[0,1]
	v_mul_f32_e32 v142, v142, v6
	v_mov_b32_e32 v3, v2
	v_mov_b32_e32 v4, v2
	v_mov_b32_e32 v5, v2
	v_mov_b32_e32 v6, v2
	v_mov_b32_e32 v7, v2
	v_mov_b32_e32 v8, v2
	v_mov_b32_e32 v9, v2
	v_mov_b32_e32 v10, v2
	v_mov_b32_e32 v11, v2
	v_mov_b32_e32 v12, v2
	v_mov_b32_e32 v13, v2
	v_mov_b32_e32 v14, v2
	v_mov_b32_e32 v15, v2
	v_mov_b32_e32 v16, v2
	v_mov_b32_e32 v17, v2
